# s5_state loads batched 8 K-steps at a time (counted waits) on top of v32
# baseline (speedup 1.0000x reference)
; #define MFMA32(a, b, c) __builtin_amdgcn_mfma_f32_32x32x16_bf16((a), (b), (c), 0, 0, 0)
; __device__ __forceinline__ void s5_state_phase(const bf16* z, const bf16* WT, const float* AL, bf16* AEXT, LAS unsigned char* lds, int tid, int G) {
;     ...
; #pragma unroll 8
;         for (int sg = 0; sg < 32; ++sg) {
;             const bf16x8 af = *(const bf16x8*)(ap + (size_t)sg * ZP); const bf16x8 bfr = *(const bf16x8*)(bp + 16 * sg);
;             acc = MFMA32(af, bfr, acc);
;             if (ni == 0) *(bf16x8*)(ae + 16 * sg) = af;
;         }
.LBB0_605:
	v_lshl_add_u64 v[40:41], v[36:37], 0, v[2:3]
	v_add_co_u32_e32 v44, vcc, 0x27e01000, v40
	v_lshl_add_u64 v[42:43], v[34:35], 0, v[2:3]
	s_nop 0
	v_addc_co_u32_e32 v45, vcc, 0, v41, vcc
	v_mov_b32_e32 v20, 0x5a00
	v_mov_b32_e32 v21, 0
	global_load_dwordx4 v[48:51], v[44:45], off
	global_load_dwordx4 v[80:83], v[42:43], off offset:-128
	v_lshl_add_u64 v[44:45], v[44:45], 0, v[20:21]
	global_load_dwordx4 v[52:55], v[44:45], off
	global_load_dwordx4 v[84:87], v[42:43], off offset:-96
	v_lshl_add_u64 v[44:45], v[44:45], 0, v[20:21]
	global_load_dwordx4 v[56:59], v[44:45], off
	global_load_dwordx4 v[88:91], v[42:43], off offset:-64
	v_lshl_add_u64 v[44:45], v[44:45], 0, v[20:21]
	global_load_dwordx4 v[60:63], v[44:45], off
	global_load_dwordx4 v[92:95], v[42:43], off offset:-32
	v_lshl_add_u64 v[44:45], v[44:45], 0, v[20:21]
	global_load_dwordx4 v[64:67], v[44:45], off
	global_load_dwordx4 v[96:99], v[42:43], off
	v_lshl_add_u64 v[44:45], v[44:45], 0, v[20:21]
	global_load_dwordx4 v[68:71], v[44:45], off
	global_load_dwordx4 v[100:103], v[42:43], off offset:32
	v_lshl_add_u64 v[44:45], v[44:45], 0, v[20:21]
	global_load_dwordx4 v[72:75], v[44:45], off
	global_load_dwordx4 v[104:107], v[42:43], off offset:64
	v_lshl_add_u64 v[44:45], v[44:45], 0, v[20:21]
	global_load_dwordx4 v[76:79], v[44:45], off
	global_load_dwordx4 v[108:111], v[42:43], off offset:96
	v_cndmask_b32_e64 v22, 0, 1, s[6:7]
	v_cmp_ne_u32_e64 s[10:11], 1, v22
	v_lshl_add_u64 v[44:45], v[38:39], 0, v[2:3]
	s_waitcnt vmcnt(14)
	v_mfma_f32_32x32x16_bf16 v[4:19], v[48:51], v[80:83], v[4:19]
	s_waitcnt vmcnt(12)
	v_mfma_f32_32x32x16_bf16 v[4:19], v[52:55], v[84:87], v[4:19]
	s_waitcnt vmcnt(10)
	v_mfma_f32_32x32x16_bf16 v[4:19], v[56:59], v[88:91], v[4:19]
	s_waitcnt vmcnt(8)
	v_mfma_f32_32x32x16_bf16 v[4:19], v[60:63], v[92:95], v[4:19]
	s_waitcnt vmcnt(6)
	v_mfma_f32_32x32x16_bf16 v[4:19], v[64:67], v[96:99], v[4:19]
	s_waitcnt vmcnt(4)
	v_mfma_f32_32x32x16_bf16 v[4:19], v[68:71], v[100:103], v[4:19]
	s_waitcnt vmcnt(2)
	v_mfma_f32_32x32x16_bf16 v[4:19], v[72:75], v[104:107], v[4:19]
	s_waitcnt vmcnt(0)
	v_mfma_f32_32x32x16_bf16 v[4:19], v[76:79], v[108:111], v[4:19]
	s_and_b64 vcc, exec, s[10:11]
	s_cbranch_vccnz .LBB0_604
	global_store_dwordx4 v[44:45], v[48:51], off offset:-128
	global_store_dwordx4 v[44:45], v[52:55], off offset:-96
	global_store_dwordx4 v[44:45], v[56:59], off offset:-64
	global_store_dwordx4 v[44:45], v[60:63], off offset:-32
	global_store_dwordx4 v[44:45], v[64:67], off
	global_store_dwordx4 v[44:45], v[68:71], off offset:32
	global_store_dwordx4 v[44:45], v[72:75], off offset:64
	global_store_dwordx4 v[44:45], v[76:79], off offset:96
	s_branch .LBB0_604
